# v81 + mlp1 (relu^2 -> bf16) GEMM epilogue: packed 16-B pieces transposed across lanes through the wave's free SA(1,1) LDS slices so 4 consecutive lanes store 64 contiguous bytes; same arithmetic
# speedup vs baseline: 1.0037x; 1.0037x over previous
; DI unsigned pk2(float lo, float hi) { f32x2 v = {lo, hi}; bf2_t r = __builtin_convertvector(v, bf2_t); return __builtin_bit_cast(unsigned, r); }
;     DI void operator()(const f32x4 (&acc)[2][2][4][2], const Unit& u, int wr, int wc, int fr, int fq) const {
;         const int row0 = u.pm * BM + wr * 64 + fr, col0 = u.pn * BM + wc * 32 + 8 * fq;
; #pragma unroll
;         for (int ai = 0; ai < 2; ++ai)
; #pragma unroll
;             for (int m = 0; m < 4; ++m) { const size_t row = (size_t)(row0 + ai * HALF + m * 16);
; #pragma unroll
;                 for (int bj = 0; bj < 2; ++bj) { const int col = col0 + bj * HALF; f32x4 v0 = acc[ai][bj][m][0], v1 = acc[ai][bj][m][1];
; #pragma unroll
;                     for (int j = 0; j < 4; ++j) { const float a = fmaxf(v0[j], 0.f), b = fmaxf(v1[j], 0.f); v0[j] = a * a; v1[j] = b * b; }
;                     u32x4 w; w.x = pk2(v0[0], v0[1]); w.y = pk2(v0[2], v0[3]); w.z = pk2(v1[0], v1[1]); w.w = pk2(v1[2], v1[3]);
;                     *(u32x4*)(U + row * FF + col) = w; } }
;     }
.LBB0_911:
	v_mbcnt_lo_u32_b32 v144, -1, 0
	v_mbcnt_hi_u32_b32 v144, -1, v144
	v_readlane_b32 s3, v253, 14
	v_readlane_b32 s16, v253, 12
	v_readlane_b32 s17, v253, 13
	v_and_b32_e32 v145, 15, v144
	v_lshrrev_b32_e32 v146, 4, v144
	v_bfe_u32 v147, v144, 2, 2
	v_xor_b32_e32 v147, v147, v146
	v_lshlrev_b32_e32 v147, 4, v147
	v_lshl_or_b32 v145, v145, 6, v147
	v_and_b32_e32 v147, 3, v144
	v_xor_b32_e32 v146, v146, v147
	v_lshlrev_b32_e32 v146, 4, v146
	v_lshrrev_b32_e32 v144, 2, v144
	v_lshl_or_b32 v146, v144, 6, v146
	s_add_i32 s18, s3, 0xc000
	v_add_u32_e32 v145, s18, v145
	v_add_u32_e32 v146, s18, v146
	v_lshlrev_b32_e32 v147, 4, v147
	v_lshl_or_b32 v147, v144, 13, v147
	s_lshr_b32 s3, s3, 10
	s_lshr_b32 s18, s3, 2
	s_and_b32 s3, s3, 3
	s_lshl_b32 s18, s18, 19
	s_lshl_b32 s3, s3, 6
	s_add_i32 s18, s18, s3
	v_add_u32_e32 v147, s18, v147
	s_lshl_b32 s18, s14, 21
	s_lshl_b32 s3, s35, 9
	s_add_u32 s18, s18, s3
	s_add_u32 s16, s16, s18
	s_addc_u32 s17, s17, 0
	v_max_f32_e32 v126, 0, v126
	v_max_f32_e32 v127, 0, v127
	v_max_f32_e32 v128, 0, v128
	v_max_f32_e32 v129, 0, v129
	v_max_f32_e32 v122, 0, v122
	v_max_f32_e32 v123, 0, v123
	v_max_f32_e32 v124, 0, v124
	v_max_f32_e32 v125, 0, v125
	v_pk_mul_f32 v[126:127], v[126:127], v[126:127]
	v_pk_mul_f32 v[128:129], v[128:129], v[128:129]
	v_pk_mul_f32 v[122:123], v[122:123], v[122:123]
	v_pk_mul_f32 v[124:125], v[124:125], v[124:125]
	v_cvt_pk_bf16_f32 v152, v126, v127
	v_cvt_pk_bf16_f32 v153, v128, v129
	v_cvt_pk_bf16_f32 v154, v122, v123
	v_cvt_pk_bf16_f32 v155, v124, v125
	ds_write_b128 v145, v[152:155]
	ds_read_b128 v[160:163], v146
	v_max_f32_e32 v118, 0, v118
	v_max_f32_e32 v119, 0, v119
	v_max_f32_e32 v120, 0, v120
	v_max_f32_e32 v121, 0, v121
	v_max_f32_e32 v114, 0, v114
	v_max_f32_e32 v115, 0, v115
	v_max_f32_e32 v116, 0, v116
	v_max_f32_e32 v117, 0, v117
	v_pk_mul_f32 v[118:119], v[118:119], v[118:119]
	v_pk_mul_f32 v[120:121], v[120:121], v[120:121]
	v_pk_mul_f32 v[114:115], v[114:115], v[114:115]
	v_pk_mul_f32 v[116:117], v[116:117], v[116:117]
	v_cvt_pk_bf16_f32 v156, v118, v119
	v_cvt_pk_bf16_f32 v157, v120, v121
	v_cvt_pk_bf16_f32 v158, v114, v115
	v_cvt_pk_bf16_f32 v159, v116, v117
	ds_write_b128 v145, v[156:159] offset:8192
	ds_read_b128 v[164:167], v146 offset:8192
	s_waitcnt lgkmcnt(2)
	global_store_dwordx4 v147, v[160:163], s[16:17]
	v_max_f32_e32 v108, 0, v108
	v_max_f32_e32 v109, 0, v109
	v_max_f32_e32 v110, 0, v110
	v_max_f32_e32 v111, 0, v111
	v_max_f32_e32 v104, 0, v104
	v_max_f32_e32 v105, 0, v105
	v_max_f32_e32 v106, 0, v106
	v_max_f32_e32 v107, 0, v107
	v_pk_mul_f32 v[108:109], v[108:109], v[108:109]
	v_pk_mul_f32 v[110:111], v[110:111], v[110:111]
	v_pk_mul_f32 v[104:105], v[104:105], v[104:105]
	v_pk_mul_f32 v[106:107], v[106:107], v[106:107]
	v_cvt_pk_bf16_f32 v152, v108, v109
	v_cvt_pk_bf16_f32 v153, v110, v111
	v_cvt_pk_bf16_f32 v154, v104, v105
	v_cvt_pk_bf16_f32 v155, v106, v107
	ds_write_b128 v145, v[152:155]
	ds_read_b128 v[168:171], v146
	s_waitcnt lgkmcnt(2)
	global_store_dwordx4 v147, v[164:167], s[16:17] offset:256
	v_max_f32_e32 v100, 0, v100
	v_max_f32_e32 v101, 0, v101
	v_max_f32_e32 v102, 0, v102
	v_max_f32_e32 v103, 0, v103
	v_max_f32_e32 v96, 0, v96
	v_max_f32_e32 v97, 0, v97
	v_max_f32_e32 v98, 0, v98
	v_max_f32_e32 v99, 0, v99
	v_pk_mul_f32 v[100:101], v[100:101], v[100:101]
	v_pk_mul_f32 v[102:103], v[102:103], v[102:103]
	v_pk_mul_f32 v[96:97], v[96:97], v[96:97]
	v_pk_mul_f32 v[98:99], v[98:99], v[98:99]
	v_cvt_pk_bf16_f32 v156, v100, v101
	v_cvt_pk_bf16_f32 v157, v102, v103
	v_cvt_pk_bf16_f32 v158, v96, v97
	v_cvt_pk_bf16_f32 v159, v98, v99
	ds_write_b128 v145, v[156:159] offset:8192
	ds_read_b128 v[172:175], v146 offset:8192
	s_waitcnt lgkmcnt(2)
	s_add_u32 s16, s16, 0x20000
	s_addc_u32 s17, s17, 0
	global_store_dwordx4 v147, v[168:171], s[16:17]
	v_max_f32_e32 v92, 0, v92
	v_max_f32_e32 v93, 0, v93
	v_max_f32_e32 v94, 0, v94
	v_max_f32_e32 v95, 0, v95
	v_max_f32_e32 v88, 0, v88
	v_max_f32_e32 v89, 0, v89
	v_max_f32_e32 v90, 0, v90
	v_max_f32_e32 v91, 0, v91
	v_pk_mul_f32 v[92:93], v[92:93], v[92:93]
	v_pk_mul_f32 v[94:95], v[94:95], v[94:95]
	v_pk_mul_f32 v[88:89], v[88:89], v[88:89]
	v_pk_mul_f32 v[90:91], v[90:91], v[90:91]
	v_cvt_pk_bf16_f32 v152, v92, v93
	v_cvt_pk_bf16_f32 v153, v94, v95
	v_cvt_pk_bf16_f32 v154, v88, v89
	v_cvt_pk_bf16_f32 v155, v90, v91
	ds_write_b128 v145, v[152:155]
	ds_read_b128 v[160:163], v146
	s_waitcnt lgkmcnt(2)
	global_store_dwordx4 v147, v[172:175], s[16:17] offset:256
	v_max_f32_e32 v84, 0, v84
	v_max_f32_e32 v85, 0, v85
	v_max_f32_e32 v86, 0, v86
	v_max_f32_e32 v87, 0, v87
	v_max_f32_e32 v80, 0, v80
	v_max_f32_e32 v81, 0, v81
	v_max_f32_e32 v82, 0, v82
	v_max_f32_e32 v83, 0, v83
	v_pk_mul_f32 v[84:85], v[84:85], v[84:85]
	v_pk_mul_f32 v[86:87], v[86:87], v[86:87]
	v_pk_mul_f32 v[80:81], v[80:81], v[80:81]
	v_pk_mul_f32 v[82:83], v[82:83], v[82:83]
	v_cvt_pk_bf16_f32 v156, v84, v85
	v_cvt_pk_bf16_f32 v157, v86, v87
	v_cvt_pk_bf16_f32 v158, v80, v81
	v_cvt_pk_bf16_f32 v159, v82, v83
	ds_write_b128 v145, v[156:159] offset:8192
	ds_read_b128 v[164:167], v146 offset:8192
	s_waitcnt lgkmcnt(2)
	s_add_u32 s16, s16, 0x20000
	s_addc_u32 s17, s17, 0
	global_store_dwordx4 v147, v[160:163], s[16:17]
	v_max_f32_e32 v76, 0, v76
	v_max_f32_e32 v77, 0, v77
	v_max_f32_e32 v78, 0, v78
	v_max_f32_e32 v79, 0, v79
	v_max_f32_e32 v72, 0, v72
	v_max_f32_e32 v73, 0, v73
	v_max_f32_e32 v74, 0, v74
	v_max_f32_e32 v75, 0, v75
	v_pk_mul_f32 v[76:77], v[76:77], v[76:77]
	v_pk_mul_f32 v[78:79], v[78:79], v[78:79]
	v_pk_mul_f32 v[72:73], v[72:73], v[72:73]
	v_pk_mul_f32 v[74:75], v[74:75], v[74:75]
	v_cvt_pk_bf16_f32 v152, v76, v77
	v_cvt_pk_bf16_f32 v153, v78, v79
	v_cvt_pk_bf16_f32 v154, v72, v73
	v_cvt_pk_bf16_f32 v155, v74, v75
	ds_write_b128 v145, v[152:155]
	ds_read_b128 v[168:171], v146
	s_waitcnt lgkmcnt(2)
; DI unsigned pk2(float lo, float hi) { f32x2 v = {lo, hi}; bf2_t r = __builtin_convertvector(v, bf2_t); return __builtin_bit_cast(unsigned, r); }
; #define PG8_BAR __builtin_amdgcn_s_barrier()
; template <class Epi>
; DI void gemm_phase(LAS unsigned char* lds, const Gemm g, const Order& S, const Epi& E, const int wv) {
;     ...
;         if (!has_next) break;
; #pragma unroll
;         for (int a = 0; a < 2; ++a)
; #pragma unroll
;             for (int b = 0; b < 2; ++b)
; #pragma unroll
;                 for (int m = 0; m < 4; ++m)
; #pragma unroll
;                     for (int n = 0; n < 2; ++n) acc[a][b][m][n] = (f32x4){0.f, 0.f, 0.f, 0.f};
;         cur = nxt; cA = nA; cB = nB; ++ui;
;         if (wr == 1) PG8_BAR;
;     DI void operator()(const f32x4 (&acc)[2][2][4][2], const Unit& u, int wr, int wc, int fr, int fq) const {
;         const int row0 = u.pm * BM + wr * 64 + fr, col0 = u.pn * BM + wc * 32 + 8 * fq;
; #pragma unroll
;         for (int ai = 0; ai < 2; ++ai)
; #pragma unroll
;             for (int m = 0; m < 4; ++m) { const size_t row = (size_t)(row0 + ai * HALF + m * 16);
; #pragma unroll
;                 for (int bj = 0; bj < 2; ++bj) { const int col = col0 + bj * HALF; f32x4 v0 = acc[ai][bj][m][0], v1 = acc[ai][bj][m][1];
; #pragma unroll
;                     for (int j = 0; j < 4; ++j) { const float a = fmaxf(v0[j], 0.f), b = fmaxf(v1[j], 0.f); v0[j] = a * a; v1[j] = b * b; }
;                     u32x4 w; w.x = pk2(v0[0], v0[1]); w.y = pk2(v0[2], v0[3]); w.z = pk2(v1[0], v1[1]); w.w = pk2(v1[2], v1[3]);
;                     *(u32x4*)(U + row * FF + col) = w; } }
;     }
	global_store_dwordx4 v147, v[164:167], s[16:17] offset:256
	v_max_f32_e32 v68, 0, v68
	v_max_f32_e32 v69, 0, v69
	v_max_f32_e32 v70, 0, v70
	v_max_f32_e32 v71, 0, v71
	v_max_f32_e32 v64, 0, v64
	v_max_f32_e32 v65, 0, v65
	v_max_f32_e32 v66, 0, v66
	v_max_f32_e32 v67, 0, v67
	v_pk_mul_f32 v[68:69], v[68:69], v[68:69]
	v_pk_mul_f32 v[70:71], v[70:71], v[70:71]
	v_pk_mul_f32 v[64:65], v[64:65], v[64:65]
	v_pk_mul_f32 v[66:67], v[66:67], v[66:67]
	v_cvt_pk_bf16_f32 v156, v68, v69
	v_cvt_pk_bf16_f32 v157, v70, v71
	v_cvt_pk_bf16_f32 v158, v64, v65
	v_cvt_pk_bf16_f32 v159, v66, v67
	ds_write_b128 v145, v[156:159] offset:8192
	ds_read_b128 v[172:175], v146 offset:8192
	s_waitcnt lgkmcnt(2)
	s_add_u32 s16, s16, 0x20000
	s_addc_u32 s17, s17, 0
	global_store_dwordx4 v147, v[168:171], s[16:17]
	v_max_f32_e32 v60, 0, v60
	v_max_f32_e32 v61, 0, v61
	v_max_f32_e32 v62, 0, v62
	v_max_f32_e32 v63, 0, v63
	v_max_f32_e32 v56, 0, v56
	v_max_f32_e32 v57, 0, v57
	v_max_f32_e32 v58, 0, v58
	v_max_f32_e32 v59, 0, v59
	v_pk_mul_f32 v[60:61], v[60:61], v[60:61]
	v_pk_mul_f32 v[62:63], v[62:63], v[62:63]
	v_pk_mul_f32 v[56:57], v[56:57], v[56:57]
	v_pk_mul_f32 v[58:59], v[58:59], v[58:59]
	v_cvt_pk_bf16_f32 v152, v60, v61
	v_cvt_pk_bf16_f32 v153, v62, v63
	v_cvt_pk_bf16_f32 v154, v56, v57
	v_cvt_pk_bf16_f32 v155, v58, v59
	ds_write_b128 v145, v[152:155]
	ds_read_b128 v[160:163], v146
	s_waitcnt lgkmcnt(2)
	global_store_dwordx4 v147, v[172:175], s[16:17] offset:256
	v_max_f32_e32 v52, 0, v52
	v_max_f32_e32 v53, 0, v53
	v_max_f32_e32 v54, 0, v54
	v_max_f32_e32 v55, 0, v55
	v_max_f32_e32 v48, 0, v48
	v_max_f32_e32 v49, 0, v49
	v_max_f32_e32 v50, 0, v50
	v_max_f32_e32 v51, 0, v51
	v_pk_mul_f32 v[52:53], v[52:53], v[52:53]
	v_pk_mul_f32 v[54:55], v[54:55], v[54:55]
	v_pk_mul_f32 v[48:49], v[48:49], v[48:49]
	v_pk_mul_f32 v[50:51], v[50:51], v[50:51]
	v_cvt_pk_bf16_f32 v156, v52, v53
	v_cvt_pk_bf16_f32 v157, v54, v55
	v_cvt_pk_bf16_f32 v158, v48, v49
	v_cvt_pk_bf16_f32 v159, v50, v51
	ds_write_b128 v145, v[156:159] offset:8192
	ds_read_b128 v[164:167], v146 offset:8192
	s_waitcnt lgkmcnt(2)
	s_add_u32 s16, s16, 0xa0000
	s_addc_u32 s17, s17, 0
	global_store_dwordx4 v147, v[160:163], s[16:17]
	v_max_f32_e32 v44, 0, v44
	v_max_f32_e32 v45, 0, v45
	v_max_f32_e32 v46, 0, v46
	v_max_f32_e32 v47, 0, v47
	v_max_f32_e32 v40, 0, v40
	v_max_f32_e32 v41, 0, v41
	v_max_f32_e32 v42, 0, v42
	v_max_f32_e32 v43, 0, v43
	v_pk_mul_f32 v[44:45], v[44:45], v[44:45]
	v_pk_mul_f32 v[46:47], v[46:47], v[46:47]
	v_pk_mul_f32 v[40:41], v[40:41], v[40:41]
	v_pk_mul_f32 v[42:43], v[42:43], v[42:43]
	v_cvt_pk_bf16_f32 v152, v44, v45
	v_cvt_pk_bf16_f32 v153, v46, v47
	v_cvt_pk_bf16_f32 v154, v40, v41
	v_cvt_pk_bf16_f32 v155, v42, v43
	ds_write_b128 v145, v[152:155]
	ds_read_b128 v[168:171], v146
	s_waitcnt lgkmcnt(2)
	global_store_dwordx4 v147, v[164:167], s[16:17] offset:256
	v_max_f32_e32 v36, 0, v36
	v_max_f32_e32 v37, 0, v37
	v_max_f32_e32 v38, 0, v38
	v_max_f32_e32 v39, 0, v39
	v_max_f32_e32 v32, 0, v32
	v_max_f32_e32 v33, 0, v33
	v_max_f32_e32 v34, 0, v34
	v_max_f32_e32 v35, 0, v35
	v_pk_mul_f32 v[36:37], v[36:37], v[36:37]
	v_pk_mul_f32 v[38:39], v[38:39], v[38:39]
	v_pk_mul_f32 v[32:33], v[32:33], v[32:33]
	v_pk_mul_f32 v[34:35], v[34:35], v[34:35]
	v_cvt_pk_bf16_f32 v156, v36, v37
	v_cvt_pk_bf16_f32 v157, v38, v39
	v_cvt_pk_bf16_f32 v158, v32, v33
	v_cvt_pk_bf16_f32 v159, v34, v35
	ds_write_b128 v145, v[156:159] offset:8192
	ds_read_b128 v[172:175], v146 offset:8192
	s_waitcnt lgkmcnt(2)
	s_add_u32 s16, s16, 0x20000
	s_addc_u32 s17, s17, 0
	global_store_dwordx4 v147, v[168:171], s[16:17]
	v_max_f32_e32 v28, 0, v28
	v_max_f32_e32 v29, 0, v29
	v_max_f32_e32 v30, 0, v30
	v_max_f32_e32 v31, 0, v31
	v_max_f32_e32 v24, 0, v24
	v_max_f32_e32 v25, 0, v25
	v_max_f32_e32 v26, 0, v26
	v_max_f32_e32 v27, 0, v27
	v_pk_mul_f32 v[28:29], v[28:29], v[28:29]
	v_pk_mul_f32 v[30:31], v[30:31], v[30:31]
	v_pk_mul_f32 v[24:25], v[24:25], v[24:25]
	v_pk_mul_f32 v[26:27], v[26:27], v[26:27]
	v_cvt_pk_bf16_f32 v152, v28, v29
	v_cvt_pk_bf16_f32 v153, v30, v31
	v_cvt_pk_bf16_f32 v154, v24, v25
	v_cvt_pk_bf16_f32 v155, v26, v27
	ds_write_b128 v145, v[152:155]
	ds_read_b128 v[160:163], v146
	s_waitcnt lgkmcnt(2)
	global_store_dwordx4 v147, v[172:175], s[16:17] offset:256
	v_max_f32_e32 v20, 0, v20
	v_max_f32_e32 v21, 0, v21
	v_max_f32_e32 v22, 0, v22
	v_max_f32_e32 v23, 0, v23
	v_max_f32_e32 v16, 0, v16
	v_max_f32_e32 v17, 0, v17
	v_max_f32_e32 v18, 0, v18
	v_max_f32_e32 v19, 0, v19
	v_pk_mul_f32 v[20:21], v[20:21], v[20:21]
	v_pk_mul_f32 v[22:23], v[22:23], v[22:23]
	v_pk_mul_f32 v[16:17], v[16:17], v[16:17]
	v_pk_mul_f32 v[18:19], v[18:19], v[18:19]
	v_cvt_pk_bf16_f32 v156, v20, v21
	v_cvt_pk_bf16_f32 v157, v22, v23
	v_cvt_pk_bf16_f32 v158, v16, v17
	v_cvt_pk_bf16_f32 v159, v18, v19
	ds_write_b128 v145, v[156:159] offset:8192
	ds_read_b128 v[164:167], v146 offset:8192
	s_waitcnt lgkmcnt(2)
	s_add_u32 s16, s16, 0x20000
	s_addc_u32 s17, s17, 0
	global_store_dwordx4 v147, v[160:163], s[16:17]
	v_max_f32_e32 v12, 0, v12
	v_max_f32_e32 v13, 0, v13
	v_max_f32_e32 v14, 0, v14
	v_max_f32_e32 v15, 0, v15
	v_max_f32_e32 v8, 0, v8
	v_max_f32_e32 v9, 0, v9
	v_max_f32_e32 v10, 0, v10
	v_max_f32_e32 v11, 0, v11
	v_pk_mul_f32 v[12:13], v[12:13], v[12:13]
	v_pk_mul_f32 v[14:15], v[14:15], v[14:15]
	v_pk_mul_f32 v[8:9], v[8:9], v[8:9]
	v_pk_mul_f32 v[10:11], v[10:11], v[10:11]
	v_cvt_pk_bf16_f32 v152, v12, v13
	v_cvt_pk_bf16_f32 v153, v14, v15
	v_cvt_pk_bf16_f32 v154, v8, v9
	v_cvt_pk_bf16_f32 v155, v10, v11
	ds_write_b128 v145, v[152:155]
	ds_read_b128 v[168:171], v146
	s_waitcnt lgkmcnt(2)
	global_store_dwordx4 v147, v[164:167], s[16:17] offset:256
	v_max_f32_e32 v4, 0, v4
	v_max_f32_e32 v5, 0, v5
	v_max_f32_e32 v6, 0, v6
	v_max_f32_e32 v7, 0, v7
	v_max_f32_e32 v0, 0, v0
	v_max_f32_e32 v1, 0, v1
	v_max_f32_e32 v2, 0, v2
	v_max_f32_e32 v3, 0, v3
	v_pk_mul_f32 v[4:5], v[4:5], v[4:5]
	v_pk_mul_f32 v[6:7], v[6:7], v[6:7]
	v_pk_mul_f32 v[0:1], v[0:1], v[0:1]
	v_pk_mul_f32 v[2:3], v[2:3], v[2:3]
	v_cvt_pk_bf16_f32 v156, v4, v5
	v_cvt_pk_bf16_f32 v157, v6, v7
	v_cvt_pk_bf16_f32 v158, v0, v1
	v_cvt_pk_bf16_f32 v159, v2, v3
	ds_write_b128 v145, v[156:159] offset:8192
	ds_read_b128 v[172:175], v146 offset:8192
	s_waitcnt lgkmcnt(2)
	s_add_u32 s16, s16, 0x20000
	s_addc_u32 s17, s17, 0
	global_store_dwordx4 v147, v[168:171], s[16:17]
	s_waitcnt lgkmcnt(0)
	global_store_dwordx4 v147, v[172:175], s[16:17] offset:256
	s_andn2_b64 vcc, exec, s[4:5]
	s_mov_b64 s[4:5], -1
	s_movk_i32 s36, 0x44
	s_cbranch_vccnz .LBB0_903
	v_readlane_b32 s4, v254, 58
	v_readlane_b32 s5, v254, 59
	s_and_b64 vcc, exec, s[4:5]
	s_cbranch_vccnz .LBB0_902
	s_barrier
	s_branch .LBB0_902
